# v31
# speedup vs baseline: 1.0020x; 1.0004x over previous
.LBB0_273:
	s_or_b64 exec, exec, s[8:9]
	s_waitcnt vmcnt(10)
	v_mul_f32_e32 v1, 0xbfb8aa3b, v76
	v_exp_f32_e32 v1, v1
	s_lshl_b32 s8, s11, 1
	s_add_u32 s8, s56, s8
	s_addc_u32 s9, s68, 0
	v_add_f32_e32 v73, 1.0, v1
	v_add_f32_e32 v2, -1.0, v73
	v_sub_f32_e32 v3, v2, v73
	v_add_f32_e32 v3, 1.0, v3
	v_sub_f32_e32 v2, v1, v2
	v_add_f32_e32 v76, v2, v3
	v_frexp_mant_f32_e32 v2, v73
	v_cmp_gt_f32_e32 vcc, s39, v2
	v_cvt_f64_f32_e32 v[2:3], v73
	v_frexp_exp_i32_f64_e32 v2, v[2:3]
	v_subbrev_co_u32_e32 v2, vcc, 0, v2, vcc
	v_sub_u32_e32 v3, 0, v2
	v_ldexp_f32 v73, v73, v3
	v_ldexp_f32 v3, v76, v3
	v_add_f32_e32 v76, -1.0, v73
	v_add_f32_e32 v77, 1.0, v76
	v_sub_f32_e32 v77, v73, v77
	v_add_f32_e32 v77, v3, v77
	v_add_f32_e32 v78, v76, v77
	v_sub_f32_e32 v76, v78, v76
	v_sub_f32_e32 v76, v77, v76
	v_add_f32_e32 v77, 1.0, v73
	v_add_f32_e32 v79, -1.0, v77
	v_sub_f32_e32 v73, v73, v79
	v_add_f32_e32 v3, v3, v73
	v_add_f32_e32 v73, v77, v3
	v_sub_f32_e32 v77, v73, v77
	v_sub_f32_e32 v3, v3, v77
	v_rcp_f32_e32 v77, v73
	v_cvt_f32_i32_e32 v2, v2
	v_cmp_neq_f32_e32 vcc, s40, v1
	v_and_b32_e32 v71, 63, v84
	v_mul_f32_e32 v79, v78, v77
	v_mul_f32_e32 v80, v73, v79
	v_fma_f32 v81, v79, v73, -v80
	v_fmac_f32_e32 v81, v79, v3
	v_add_f32_e32 v82, v80, v81
	v_sub_f32_e32 v83, v78, v82
	v_sub_f32_e32 v78, v78, v83
	v_sub_f32_e32 v80, v82, v80
	v_sub_f32_e32 v78, v78, v82
	v_add_f32_e32 v76, v76, v78
	v_sub_f32_e32 v78, v80, v81
	v_add_f32_e32 v76, v78, v76
	v_add_f32_e32 v78, v83, v76
	v_mul_f32_e32 v80, v77, v78
	v_mul_f32_e32 v81, v73, v80
	v_fma_f32 v73, v80, v73, -v81
	v_fmac_f32_e32 v73, v80, v3
	v_sub_f32_e32 v3, v83, v78
	v_add_f32_e32 v3, v76, v3
	v_add_f32_e32 v76, v81, v73
	v_sub_f32_e32 v82, v78, v76
	v_sub_f32_e32 v78, v78, v82
	v_sub_f32_e32 v81, v76, v81
	v_sub_f32_e32 v76, v78, v76
	v_add_f32_e32 v3, v3, v76
	v_sub_f32_e32 v73, v81, v73
	v_add_f32_e32 v3, v73, v3
	v_add_f32_e32 v73, v79, v80
	v_add_f32_e32 v3, v82, v3
	v_sub_f32_e32 v76, v73, v79
	v_mul_f32_e32 v3, v77, v3
	v_sub_f32_e32 v76, v80, v76
	v_add_f32_e32 v3, v76, v3
	v_mul_f32_e32 v79, 0x3f317218, v2
	v_add_f32_e32 v76, v73, v3
	v_fma_f32 v80, v2, s62, -v79
	v_mul_f32_e32 v77, v76, v76
	v_fmac_f32_e32 v80, 0xb102e308, v2
	v_sub_f32_e32 v2, v76, v73
	v_fmamk_f32 v78, v77, 0x3e9b6dac, v236
	v_sub_f32_e32 v2, v3, v2
	v_add_f32_e32 v3, v79, v80
	v_fmaak_f32 v78, v77, v78, 0x3f2aaada
	v_sub_f32_e32 v73, v3, v79
	v_ldexp_f32 v79, v76, 1
	v_mul_f32_e32 v76, v76, v77
	v_mul_f32_e32 v76, v76, v78
	v_add_f32_e32 v77, v79, v76
	v_sub_f32_e32 v78, v77, v79
	v_ldexp_f32 v2, v2, 1
	v_sub_f32_e32 v76, v76, v78
	v_add_f32_e32 v2, v2, v76
	v_add_f32_e32 v76, v77, v2
	v_sub_f32_e32 v77, v76, v77
	v_sub_f32_e32 v2, v2, v77
	v_add_f32_e32 v77, v3, v76
	v_sub_f32_e32 v78, v77, v3
	v_sub_f32_e32 v79, v77, v78
	v_sub_f32_e32 v73, v80, v73
	v_sub_f32_e32 v3, v3, v79
	v_sub_f32_e32 v76, v76, v78
	v_add_f32_e32 v3, v76, v3
	v_add_f32_e32 v76, v73, v2
	v_sub_f32_e32 v78, v76, v73
	v_sub_f32_e32 v79, v76, v78
	v_sub_f32_e32 v73, v73, v79
	v_sub_f32_e32 v2, v2, v78
	v_add_f32_e32 v3, v76, v3
	v_add_f32_e32 v2, v2, v73
	v_add_f32_e32 v73, v77, v3
	v_sub_f32_e32 v76, v73, v77
	v_sub_f32_e32 v3, v3, v76
	v_add_f32_e32 v2, v2, v3
	v_add_f32_e32 v2, v73, v2
	v_cndmask_b32_e32 v2, v219, v2, vcc
	v_cmp_ngt_f32_e32 vcc, -1.0, v1
	s_add_u32 s8, s8, s10
	s_addc_u32 s9, s9, 0
	v_cndmask_b32_e32 v2, v220, v2, vcc
	v_cmp_neq_f32_e32 vcc, -1.0, v1
	v_lshlrev_b32_e32 v76, 1, v71
	v_mov_b32_e32 v77, v0
	v_cndmask_b32_e32 v2, v221, v2, vcc
	v_cmp_lt_f32_e64 vcc, |v1|, s28
	v_lshl_add_u64 v[90:91], s[8:9], 0, v[76:77]
	s_movk_i32 s8, 0x90
	v_cndmask_b32_e32 v1, v2, v1, vcc
	v_lshlrev_b32_e32 v2, 3, v85
	v_ashrrev_i32_e32 v3, 31, v2
	v_lshlrev_b64 v[76:77], 11, v[2:3]
	v_lshl_add_u64 v[76:77], v[90:91], 0, v[76:77]
	global_load_ushort v3, v[76:77], off
	v_or_b32_e32 v76, 1, v2
	v_ashrrev_i32_e32 v77, 31, v76
	v_lshlrev_b64 v[76:77], 11, v[76:77]
	v_lshl_add_u64 v[76:77], v[90:91], 0, v[76:77]
	global_load_ushort v87, v[76:77], off
	v_or_b32_e32 v76, 2, v2
	v_ashrrev_i32_e32 v77, 31, v76
	v_lshlrev_b64 v[76:77], 11, v[76:77]
	v_lshl_add_u64 v[76:77], v[90:91], 0, v[76:77]
	global_load_ushort v126, v[76:77], off
	v_or_b32_e32 v76, 3, v2
	v_ashrrev_i32_e32 v77, 31, v76
	v_lshlrev_b64 v[76:77], 11, v[76:77]
	v_lshl_add_u64 v[76:77], v[90:91], 0, v[76:77]
	global_load_ushort v127, v[76:77], off
	v_or_b32_e32 v76, 4, v2
	v_ashrrev_i32_e32 v77, 31, v76
	v_lshlrev_b64 v[76:77], 11, v[76:77]
	v_lshl_add_u64 v[76:77], v[90:91], 0, v[76:77]
	global_load_ushort v128, v[76:77], off
	v_or_b32_e32 v76, 5, v2
	v_ashrrev_i32_e32 v77, 31, v76
	v_lshlrev_b64 v[76:77], 11, v[76:77]
	v_lshl_add_u64 v[76:77], v[90:91], 0, v[76:77]
	global_load_ushort v129, v[76:77], off
	v_or_b32_e32 v76, 6, v2
	v_ashrrev_i32_e32 v77, 31, v76
	v_lshlrev_b64 v[76:77], 11, v[76:77]
	v_lshl_add_u64 v[76:77], v[90:91], 0, v[76:77]
	global_load_ushort v130, v[76:77], off
	v_or_b32_e32 v76, 7, v2
	v_ashrrev_i32_e32 v77, 31, v76
	v_lshlrev_b64 v[76:77], 11, v[76:77]
	v_lshl_add_u64 v[76:77], v[90:91], 0, v[76:77]
	global_load_ushort v131, v[76:77], off
	v_mov_b32_e32 v77, 0x6400
	v_cndmask_b32_e64 v77, v217, v77, s[6:7]
	v_lshlrev_b32_e32 v71, 2, v71
	v_mul_lo_u32 v73, v86, s8
	v_add_u32_e32 v77, 0, v77
	v_and_b32_e32 v78, 48, v84
	v_lshl_add_u32 v69, v69, 2, 0
	v_add_u32_e32 v73, 0, v73
	v_lshlrev_b32_e32 v76, 8, v86
	v_add_u32_e32 v78, 0, v78
	v_lshlrev_b32_e32 v75, 10, v75
	v_add3_u32 v68, v77, v70, v68
	v_mul_u32_u24_e32 v70, 0x90, v74
	v_lshl_or_b32 v74, v85, 11, v71
	v_readlane_b32 s12, v255, 6
	s_mov_b32 s52, 0
	v_mul_f32_e32 v1, 0xc1000000, v1
	v_add_u32_e32 v132, 0, v71
	v_add_u32_e32 v133, 61, v86
	v_add_u32_e32 v134, 64, v2
	v_cmp_lt_i32_e64 s[8:9], 0, v85
	v_cmp_eq_u32_e64 s[10:11], 7, v85
	v_add_u32_e32 v135, 0, v74
	v_add_u32_e32 v136, s12, v71
	v_add_u32_e32 v137, v73, v72
	v_add_u32_e32 v138, v69, v76
	v_add_u32_e32 v139, v78, v70
	v_add_u32_e32 v140, v68, v75
	v_lshlrev_b32_e32 v150, 11, v2
	v_mov_b32_e32 v151, v0
	v_lshl_add_u64 v[152:153], v[90:91], 0, v[150:151]
	s_mov_b64 s[82:83], 0x1000
	v_lshl_add_u64 v[154:155], v[152:153], 0, s[82:83]
	v_lshl_add_u64 v[156:157], v[154:155], 0, s[82:83]
	v_lshl_add_u64 v[158:159], v[156:157], 0, s[82:83]
	s_mov_b64 s[82:83], 0x20000
	s_waitcnt vmcnt(0)
	s_branch .LBB0_275

.LBB0_275:
	s_lshl_b32 s65, s52, 6
	s_cmp_lt_u32 s52, 31
	s_cselect_b64 s[12:13], -1, 0
	s_cmp_gt_u32 s52, 30
	s_cbranch_scc1 .LBB0_277
	v_add_u32_e32 v68, s65, v133
	v_ashrrev_i32_e32 v69, 31, v68
	v_lshlrev_b64 v[68:69], 11, v[68:69]
	v_lshl_add_u64 v[76:77], v[88:89], 0, v[68:69]
	v_add_co_u32_e32 v80, vcc, 0x1000, v76
	s_nop 0
	v_addc_co_u32_e32 v81, vcc, 0, v77, vcc
	global_load_dwordx4 v[68:71], v[76:77], off
	global_load_dwordx4 v[72:75], v[76:77], off offset:2048
	s_nop 0
	global_load_dwordx4 v[76:79], v[80:81], off
	s_nop 0
	global_load_dwordx4 v[80:83], v[80:81], off offset:2048
	s_nop 0
	v_lshl_add_u64 v[160:161], v[152:153], 0, s[82:83]
	v_lshl_add_u64 v[162:163], v[154:155], 0, s[82:83]
	v_lshl_add_u64 v[164:165], v[156:157], 0, s[82:83]
	v_lshl_add_u64 v[166:167], v[158:159], 0, s[82:83]
	global_load_ushort v141, v[160:161], off
	global_load_ushort v142, v[160:161], off offset:2048
	global_load_ushort v143, v[162:163], off
	global_load_ushort v144, v[162:163], off offset:2048
	global_load_ushort v145, v[164:165], off
	global_load_ushort v146, v[164:165], off offset:2048
	global_load_ushort v147, v[166:167], off
	global_load_ushort v148, v[166:167], off offset:2048

.LBB0_289:
	s_or_b64 exec, exec, s[16:17]
	s_waitcnt lgkmcnt(0)
	v_fmac_f32_e32 v95, v92, v108
	s_waitcnt vmcnt(7)
	v_lshlrev_b32_e32 v92, 16, v3
	v_mul_f32_e32 v92, v95, v92
	v_cvt_pk_bf16_f32 v92, v92, v0
	global_store_short v[152:153], v92, off
	v_fmac_f32_e32 v93, v98, v108
	s_waitcnt vmcnt(7)
	v_lshlrev_b32_e32 v92, 16, v87
	v_mul_f32_e32 v92, v93, v92
	v_cvt_pk_bf16_f32 v92, v92, v0
	global_store_short v[152:153], v92, off offset:2048
	v_fmac_f32_e32 v94, v101, v108
	s_waitcnt vmcnt(7)
	v_lshlrev_b32_e32 v95, 16, v126
	v_mul_f32_e32 v94, v94, v95
	v_cvt_pk_bf16_f32 v94, v94, v0
	global_store_short v[154:155], v94, off
	v_fmac_f32_e32 v96, v103, v108
	s_waitcnt vmcnt(7)
	v_lshlrev_b32_e32 v94, 16, v127
	v_mul_f32_e32 v94, v96, v94
	v_cvt_pk_bf16_f32 v94, v94, v0
	global_store_short v[154:155], v94, off offset:2048
	v_fmac_f32_e32 v97, v104, v108
	s_waitcnt vmcnt(7)
	v_lshlrev_b32_e32 v94, 16, v128
	v_mul_f32_e32 v94, v97, v94
	v_cvt_pk_bf16_f32 v94, v94, v0
	global_store_short v[156:157], v94, off
	v_fmac_f32_e32 v99, v105, v108
	s_waitcnt vmcnt(7)
	v_lshlrev_b32_e32 v94, 16, v129
	v_mul_f32_e32 v94, v99, v94
	v_cvt_pk_bf16_f32 v94, v94, v0
	global_store_short v[156:157], v94, off offset:2048
	v_fmac_f32_e32 v102, v107, v108
	s_waitcnt vmcnt(7)
	v_lshlrev_b32_e32 v94, 16, v130
	v_mul_f32_e32 v94, v102, v94
	v_cvt_pk_bf16_f32 v94, v94, v0
	global_store_short v[158:159], v94, off
	v_fmac_f32_e32 v100, v106, v108
	s_waitcnt vmcnt(7)
	v_lshlrev_b32_e32 v94, 16, v131
	s_add_i32 s52, s52, 1
	v_mul_f32_e32 v94, v100, v94
	v_cvt_pk_bf16_f32 v94, v94, v0
	global_store_short v[158:159], v94, off offset:2048
	v_lshl_add_u64 v[152:153], v[152:153], 0, s[82:83]
	v_lshl_add_u64 v[154:155], v[154:155], 0, s[82:83]
	v_lshl_add_u64 v[156:157], v[156:157], 0, s[82:83]
	v_lshl_add_u64 v[158:159], v[158:159], 0, s[82:83]
	s_and_saveexec_b64 s[16:17], s[10:11]
	s_cbranch_execnz .LBB0_291
	s_or_b64 exec, exec, s[16:17]
	s_and_b64 vcc, exec, s[12:13]
	s_cbranch_vccz .LBB0_274
	s_branch .LBB0_292
